# P1 epilogue: straight-line fast path for the plain (q, k, p_in) column tiles, SGPR-base stores with 32-bit offsets
# speedup vs baseline: 1.0063x; 1.0063x over previous
.LBB0_135:
	s_ashr_i32 s73, s46, 1
	s_and_b32 s71, s46, 1
	s_cmp_lt_u32 s46, 4
	s_cbranch_scc1 .Lepi_plain
	s_cmp_eq_u32 s73, 4
	s_cbranch_scc1 .Lepi_plain
	s_lshl_b32 s30, s48, 8
	s_cmp_eq_u32 s57, 2
	s_cselect_b32 s47, 0x80, 0
	s_add_i32 s57, s30, s60
	s_add_i32 s57, s57, s47
	s_cmp_lg_u32 s73, 2
	s_mov_b64 s[48:49], -1
	s_cbranch_scc0 .LBB0_324
	s_cmp_lt_u32 s46, 2
	s_cbranch_scc1 .LBB0_148
	s_cmp_lt_i32 s73, 5
	s_cbranch_scc1 .LBB0_149
	s_mov_b64 s[84:85], 0
	s_cmp_gt_i32 s73, 5
	s_mov_b64 s[46:47], 0
	s_mov_b64 s[50:51], -1
	s_cbranch_scc0 .LBB0_146
	s_cmp_gt_i32 s73, 6
	s_cbranch_scc0 .LBB0_143
	s_cmp_eq_u32 s73, 7
	s_mov_b64 s[46:47], -1
	s_cbranch_scc0 .LBB0_142
	s_mov_b64 s[46:47], 0

.Lepi_plain:
	s_lshl_b32 s30, s48, 8
	s_cmp_eq_u32 s57, 2
	s_cselect_b32 s47, 0x80, 0
	s_add_i32 s30, s30, s60
	s_add_i32 s30, s30, s47
	s_cmp_lg_u32 s57, 0
	s_cselect_b32 s47, 1, 0
	v_readlane_b32 s50, v240, 9
	v_readlane_b32 s51, v240, 10
	s_movk_i32 s82, 0x1400
	s_lshl_b32 s83, s71, 9
	s_cmp_eq_u32 s73, 4
	s_cselect_b32 s81, 0x800, 0
	s_add_i32 s83, s83, s81
	s_cmp_eq_u32 s73, 0
	s_cbranch_scc0 .Lepi_plain_go
	s_mov_b64 s[50:51], s[26:27]
	s_movk_i32 s82, 0xc00
.Lepi_plain_go:
	v_add_u32_e32 v133, s30, v232
	v_lshl_add_u32 v134, v234, 1, s83
	v_mad_u32_u24 v132, v133, s82, v134
	s_lshl_b32 s81, s82, 4
	s_mov_b32 s80, 0x3e38aa3b
	s_mov_b32 s83, 0x3e38aa3b
	s_cmp_eq_u32 s73, 0
	s_cbranch_scc0 .Lepi_plain_ns
	v_pk_mul_f32 v[128:129], v[128:129], s[80:81] op_sel_hi:[1,0]
	v_pk_mul_f32 v[130:131], v[130:131], s[80:81] op_sel_hi:[1,0]
	v_pk_mul_f32 v[120:121], v[120:121], s[80:81] op_sel_hi:[1,0]
	v_pk_mul_f32 v[122:123], v[122:123], s[80:81] op_sel_hi:[1,0]
	v_cvt_pk_bf16_f32 v136, v128, v129
	v_cvt_pk_bf16_f32 v137, v130, v131
	v_cvt_pk_bf16_f32 v138, v120, v121
	v_cvt_pk_bf16_f32 v139, v122, v123
	global_store_dwordx4 v132, v[136:139], s[50:51] sc1
	v_pk_mul_f32 v[112:113], v[112:113], s[80:81] op_sel_hi:[1,0]
	v_pk_mul_f32 v[114:115], v[114:115], s[80:81] op_sel_hi:[1,0]
	v_pk_mul_f32 v[104:105], v[104:105], s[80:81] op_sel_hi:[1,0]
	v_pk_mul_f32 v[106:107], v[106:107], s[80:81] op_sel_hi:[1,0]
	v_cvt_pk_bf16_f32 v140, v112, v113
	v_cvt_pk_bf16_f32 v141, v114, v115
	v_cvt_pk_bf16_f32 v142, v104, v105
	v_cvt_pk_bf16_f32 v143, v106, v107
	global_store_dwordx4 v132, v[140:143], s[50:51] offset:256 sc1
	v_add_u32_e32 v132, s81, v132
	v_pk_mul_f32 v[124:125], v[124:125], s[80:81] op_sel_hi:[1,0]
	v_pk_mul_f32 v[126:127], v[126:127], s[80:81] op_sel_hi:[1,0]
	v_pk_mul_f32 v[116:117], v[116:117], s[80:81] op_sel_hi:[1,0]
	v_pk_mul_f32 v[118:119], v[118:119], s[80:81] op_sel_hi:[1,0]
	v_cvt_pk_bf16_f32 v136, v124, v125
	v_cvt_pk_bf16_f32 v137, v126, v127
	v_cvt_pk_bf16_f32 v138, v116, v117
	v_cvt_pk_bf16_f32 v139, v118, v119
	global_store_dwordx4 v132, v[136:139], s[50:51] sc1
	v_pk_mul_f32 v[108:109], v[108:109], s[80:81] op_sel_hi:[1,0]
	v_pk_mul_f32 v[110:111], v[110:111], s[80:81] op_sel_hi:[1,0]
	v_pk_mul_f32 v[100:101], v[100:101], s[80:81] op_sel_hi:[1,0]
	v_pk_mul_f32 v[102:103], v[102:103], s[80:81] op_sel_hi:[1,0]
	v_cvt_pk_bf16_f32 v140, v108, v109
	v_cvt_pk_bf16_f32 v141, v110, v111
	v_cvt_pk_bf16_f32 v142, v100, v101
	v_cvt_pk_bf16_f32 v143, v102, v103
	global_store_dwordx4 v132, v[140:143], s[50:51] offset:256 sc1
	v_add_u32_e32 v132, s81, v132
	v_pk_mul_f32 v[96:97], v[96:97], s[80:81] op_sel_hi:[1,0]
	v_pk_mul_f32 v[98:99], v[98:99], s[80:81] op_sel_hi:[1,0]
	v_pk_mul_f32 v[88:89], v[88:89], s[80:81] op_sel_hi:[1,0]
	v_pk_mul_f32 v[90:91], v[90:91], s[80:81] op_sel_hi:[1,0]
	v_cvt_pk_bf16_f32 v136, v96, v97
	v_cvt_pk_bf16_f32 v137, v98, v99
	v_cvt_pk_bf16_f32 v138, v88, v89
	v_cvt_pk_bf16_f32 v139, v90, v91
	global_store_dwordx4 v132, v[136:139], s[50:51] sc1
	v_pk_mul_f32 v[80:81], v[80:81], s[80:81] op_sel_hi:[1,0]
	v_pk_mul_f32 v[82:83], v[82:83], s[80:81] op_sel_hi:[1,0]
	v_pk_mul_f32 v[72:73], v[72:73], s[80:81] op_sel_hi:[1,0]
	v_pk_mul_f32 v[74:75], v[74:75], s[80:81] op_sel_hi:[1,0]
	v_cvt_pk_bf16_f32 v140, v80, v81
	v_cvt_pk_bf16_f32 v141, v82, v83
	v_cvt_pk_bf16_f32 v142, v72, v73
	v_cvt_pk_bf16_f32 v143, v74, v75
	global_store_dwordx4 v132, v[140:143], s[50:51] offset:256 sc1
	v_add_u32_e32 v132, s81, v132
	v_pk_mul_f32 v[92:93], v[92:93], s[80:81] op_sel_hi:[1,0]
	v_pk_mul_f32 v[94:95], v[94:95], s[80:81] op_sel_hi:[1,0]
	v_pk_mul_f32 v[84:85], v[84:85], s[80:81] op_sel_hi:[1,0]
	v_pk_mul_f32 v[86:87], v[86:87], s[80:81] op_sel_hi:[1,0]
	v_cvt_pk_bf16_f32 v136, v92, v93
	v_cvt_pk_bf16_f32 v137, v94, v95
	v_cvt_pk_bf16_f32 v138, v84, v85
	v_cvt_pk_bf16_f32 v139, v86, v87
	global_store_dwordx4 v132, v[136:139], s[50:51] sc1
	v_pk_mul_f32 v[76:77], v[76:77], s[80:81] op_sel_hi:[1,0]
	v_pk_mul_f32 v[78:79], v[78:79], s[80:81] op_sel_hi:[1,0]
	v_pk_mul_f32 v[68:69], v[68:69], s[80:81] op_sel_hi:[1,0]
	v_pk_mul_f32 v[70:71], v[70:71], s[80:81] op_sel_hi:[1,0]
	v_cvt_pk_bf16_f32 v140, v76, v77
	v_cvt_pk_bf16_f32 v141, v78, v79
	v_cvt_pk_bf16_f32 v142, v68, v69
	v_cvt_pk_bf16_f32 v143, v70, v71
	global_store_dwordx4 v132, v[140:143], s[50:51] offset:256 sc1
	s_mul_i32 s30, s81, 5
	v_add_u32_e32 v132, s30, v132
	s_cmp_lg_u32 s47, 0
	s_cbranch_scc1 .LBB0_326
	v_pk_mul_f32 v[64:65], v[64:65], s[80:81] op_sel_hi:[1,0]
	v_pk_mul_f32 v[66:67], v[66:67], s[80:81] op_sel_hi:[1,0]
	v_pk_mul_f32 v[56:57], v[56:57], s[80:81] op_sel_hi:[1,0]
	v_pk_mul_f32 v[58:59], v[58:59], s[80:81] op_sel_hi:[1,0]
	v_cvt_pk_bf16_f32 v136, v64, v65
	v_cvt_pk_bf16_f32 v137, v66, v67
	v_cvt_pk_bf16_f32 v138, v56, v57
	v_cvt_pk_bf16_f32 v139, v58, v59
	global_store_dwordx4 v132, v[136:139], s[50:51] sc1
	v_pk_mul_f32 v[48:49], v[48:49], s[80:81] op_sel_hi:[1,0]
	v_pk_mul_f32 v[50:51], v[50:51], s[80:81] op_sel_hi:[1,0]
	v_pk_mul_f32 v[40:41], v[40:41], s[80:81] op_sel_hi:[1,0]
	v_pk_mul_f32 v[42:43], v[42:43], s[80:81] op_sel_hi:[1,0]
	v_cvt_pk_bf16_f32 v140, v48, v49
	v_cvt_pk_bf16_f32 v141, v50, v51
	v_cvt_pk_bf16_f32 v142, v40, v41
	v_cvt_pk_bf16_f32 v143, v42, v43
	global_store_dwordx4 v132, v[140:143], s[50:51] offset:256 sc1
	v_add_u32_e32 v132, s81, v132
	v_pk_mul_f32 v[60:61], v[60:61], s[80:81] op_sel_hi:[1,0]
	v_pk_mul_f32 v[62:63], v[62:63], s[80:81] op_sel_hi:[1,0]
	v_pk_mul_f32 v[52:53], v[52:53], s[80:81] op_sel_hi:[1,0]
	v_pk_mul_f32 v[54:55], v[54:55], s[80:81] op_sel_hi:[1,0]
	v_cvt_pk_bf16_f32 v136, v60, v61
	v_cvt_pk_bf16_f32 v137, v62, v63
	v_cvt_pk_bf16_f32 v138, v52, v53
	v_cvt_pk_bf16_f32 v139, v54, v55
	global_store_dwordx4 v132, v[136:139], s[50:51] sc1
	v_pk_mul_f32 v[44:45], v[44:45], s[80:81] op_sel_hi:[1,0]
	v_pk_mul_f32 v[46:47], v[46:47], s[80:81] op_sel_hi:[1,0]
	v_pk_mul_f32 v[36:37], v[36:37], s[80:81] op_sel_hi:[1,0]
	v_pk_mul_f32 v[38:39], v[38:39], s[80:81] op_sel_hi:[1,0]
	v_cvt_pk_bf16_f32 v140, v44, v45
	v_cvt_pk_bf16_f32 v141, v46, v47
	v_cvt_pk_bf16_f32 v142, v36, v37
	v_cvt_pk_bf16_f32 v143, v38, v39
	global_store_dwordx4 v132, v[140:143], s[50:51] offset:256 sc1
	v_add_u32_e32 v132, s81, v132
	v_pk_mul_f32 v[32:33], v[32:33], s[80:81] op_sel_hi:[1,0]
	v_pk_mul_f32 v[34:35], v[34:35], s[80:81] op_sel_hi:[1,0]
	v_pk_mul_f32 v[24:25], v[24:25], s[80:81] op_sel_hi:[1,0]
	v_pk_mul_f32 v[26:27], v[26:27], s[80:81] op_sel_hi:[1,0]
	v_cvt_pk_bf16_f32 v136, v32, v33
	v_cvt_pk_bf16_f32 v137, v34, v35
	v_cvt_pk_bf16_f32 v138, v24, v25
	v_cvt_pk_bf16_f32 v139, v26, v27
	global_store_dwordx4 v132, v[136:139], s[50:51] sc1
	v_pk_mul_f32 v[16:17], v[16:17], s[80:81] op_sel_hi:[1,0]
	v_pk_mul_f32 v[18:19], v[18:19], s[80:81] op_sel_hi:[1,0]
	v_pk_mul_f32 v[8:9], v[8:9], s[80:81] op_sel_hi:[1,0]
	v_pk_mul_f32 v[10:11], v[10:11], s[80:81] op_sel_hi:[1,0]
	v_cvt_pk_bf16_f32 v140, v16, v17
	v_cvt_pk_bf16_f32 v141, v18, v19
	v_cvt_pk_bf16_f32 v142, v8, v9
	v_cvt_pk_bf16_f32 v143, v10, v11
	global_store_dwordx4 v132, v[140:143], s[50:51] offset:256 sc1
	v_add_u32_e32 v132, s81, v132
	v_pk_mul_f32 v[28:29], v[28:29], s[80:81] op_sel_hi:[1,0]
	v_pk_mul_f32 v[30:31], v[30:31], s[80:81] op_sel_hi:[1,0]
	v_pk_mul_f32 v[20:21], v[20:21], s[80:81] op_sel_hi:[1,0]
	v_pk_mul_f32 v[22:23], v[22:23], s[80:81] op_sel_hi:[1,0]
	v_cvt_pk_bf16_f32 v136, v28, v29
	v_cvt_pk_bf16_f32 v137, v30, v31
	v_cvt_pk_bf16_f32 v138, v20, v21
	v_cvt_pk_bf16_f32 v139, v22, v23
	global_store_dwordx4 v132, v[136:139], s[50:51] sc1
	v_pk_mul_f32 v[12:13], v[12:13], s[80:81] op_sel_hi:[1,0]
	v_pk_mul_f32 v[14:15], v[14:15], s[80:81] op_sel_hi:[1,0]
	v_pk_mul_f32 v[4:5], v[4:5], s[80:81] op_sel_hi:[1,0]
	v_pk_mul_f32 v[6:7], v[6:7], s[80:81] op_sel_hi:[1,0]
	v_cvt_pk_bf16_f32 v140, v12, v13
	v_cvt_pk_bf16_f32 v141, v14, v15
	v_cvt_pk_bf16_f32 v142, v4, v5
	v_cvt_pk_bf16_f32 v143, v6, v7
	global_store_dwordx4 v132, v[140:143], s[50:51] offset:256 sc1
	s_branch .LBB0_326
.Lepi_plain_ns:
	v_cvt_pk_bf16_f32 v136, v128, v129
	v_cvt_pk_bf16_f32 v137, v130, v131
	v_cvt_pk_bf16_f32 v138, v120, v121
	v_cvt_pk_bf16_f32 v139, v122, v123
	global_store_dwordx4 v132, v[136:139], s[50:51] sc1
	v_cvt_pk_bf16_f32 v140, v112, v113
	v_cvt_pk_bf16_f32 v141, v114, v115
	v_cvt_pk_bf16_f32 v142, v104, v105
	v_cvt_pk_bf16_f32 v143, v106, v107
	global_store_dwordx4 v132, v[140:143], s[50:51] offset:256 sc1
	v_add_u32_e32 v132, s81, v132
	v_cvt_pk_bf16_f32 v136, v124, v125
	v_cvt_pk_bf16_f32 v137, v126, v127
	v_cvt_pk_bf16_f32 v138, v116, v117
	v_cvt_pk_bf16_f32 v139, v118, v119
	global_store_dwordx4 v132, v[136:139], s[50:51] sc1
	v_cvt_pk_bf16_f32 v140, v108, v109
	v_cvt_pk_bf16_f32 v141, v110, v111
	v_cvt_pk_bf16_f32 v142, v100, v101
	v_cvt_pk_bf16_f32 v143, v102, v103
	global_store_dwordx4 v132, v[140:143], s[50:51] offset:256 sc1
	v_add_u32_e32 v132, s81, v132
	v_cvt_pk_bf16_f32 v136, v96, v97
	v_cvt_pk_bf16_f32 v137, v98, v99
	v_cvt_pk_bf16_f32 v138, v88, v89
	v_cvt_pk_bf16_f32 v139, v90, v91
	global_store_dwordx4 v132, v[136:139], s[50:51] sc1
	v_cvt_pk_bf16_f32 v140, v80, v81
	v_cvt_pk_bf16_f32 v141, v82, v83
	v_cvt_pk_bf16_f32 v142, v72, v73
	v_cvt_pk_bf16_f32 v143, v74, v75
	global_store_dwordx4 v132, v[140:143], s[50:51] offset:256 sc1
	v_add_u32_e32 v132, s81, v132
	v_cvt_pk_bf16_f32 v136, v92, v93
	v_cvt_pk_bf16_f32 v137, v94, v95
	v_cvt_pk_bf16_f32 v138, v84, v85
	v_cvt_pk_bf16_f32 v139, v86, v87
	global_store_dwordx4 v132, v[136:139], s[50:51] sc1
	v_cvt_pk_bf16_f32 v140, v76, v77
	v_cvt_pk_bf16_f32 v141, v78, v79
	v_cvt_pk_bf16_f32 v142, v68, v69
	v_cvt_pk_bf16_f32 v143, v70, v71
	global_store_dwordx4 v132, v[140:143], s[50:51] offset:256 sc1
	s_mul_i32 s30, s81, 5
	v_add_u32_e32 v132, s30, v132
	s_cmp_lg_u32 s47, 0
	s_cbranch_scc1 .LBB0_326
	v_cvt_pk_bf16_f32 v136, v64, v65
	v_cvt_pk_bf16_f32 v137, v66, v67
	v_cvt_pk_bf16_f32 v138, v56, v57
	v_cvt_pk_bf16_f32 v139, v58, v59
	global_store_dwordx4 v132, v[136:139], s[50:51] sc1
	v_cvt_pk_bf16_f32 v140, v48, v49
	v_cvt_pk_bf16_f32 v141, v50, v51
	v_cvt_pk_bf16_f32 v142, v40, v41
	v_cvt_pk_bf16_f32 v143, v42, v43
	global_store_dwordx4 v132, v[140:143], s[50:51] offset:256 sc1
	v_add_u32_e32 v132, s81, v132
	v_cvt_pk_bf16_f32 v136, v60, v61
	v_cvt_pk_bf16_f32 v137, v62, v63
	v_cvt_pk_bf16_f32 v138, v52, v53
	v_cvt_pk_bf16_f32 v139, v54, v55
	global_store_dwordx4 v132, v[136:139], s[50:51] sc1
	v_cvt_pk_bf16_f32 v140, v44, v45
	v_cvt_pk_bf16_f32 v141, v46, v47
	v_cvt_pk_bf16_f32 v142, v36, v37
	v_cvt_pk_bf16_f32 v143, v38, v39
	global_store_dwordx4 v132, v[140:143], s[50:51] offset:256 sc1
	v_add_u32_e32 v132, s81, v132
	v_cvt_pk_bf16_f32 v136, v32, v33
	v_cvt_pk_bf16_f32 v137, v34, v35
	v_cvt_pk_bf16_f32 v138, v24, v25
	v_cvt_pk_bf16_f32 v139, v26, v27
	global_store_dwordx4 v132, v[136:139], s[50:51] sc1
	v_cvt_pk_bf16_f32 v140, v16, v17
	v_cvt_pk_bf16_f32 v141, v18, v19
	v_cvt_pk_bf16_f32 v142, v8, v9
	v_cvt_pk_bf16_f32 v143, v10, v11
	global_store_dwordx4 v132, v[140:143], s[50:51] offset:256 sc1
	v_add_u32_e32 v132, s81, v132
	v_cvt_pk_bf16_f32 v136, v28, v29
	v_cvt_pk_bf16_f32 v137, v30, v31
	v_cvt_pk_bf16_f32 v138, v20, v21
	v_cvt_pk_bf16_f32 v139, v22, v23
	global_store_dwordx4 v132, v[136:139], s[50:51] sc1
	v_cvt_pk_bf16_f32 v140, v12, v13
	v_cvt_pk_bf16_f32 v141, v14, v15
	v_cvt_pk_bf16_f32 v142, v4, v5
	v_cvt_pk_bf16_f32 v143, v6, v7
	global_store_dwordx4 v132, v[140:143], s[50:51] offset:256 sc1
	s_branch .LBB0_326
